# hand-written EpiPle with permlane32_swap store swizzle: each store instruction writes contiguous 64-B half lines instead of 16-B pieces at 32-B stride
# baseline (speedup 1.0000x reference)
; __device__ __forceinline__ void row_rs8(const float* SS, int row0, int fq, float (&rsv)[2][4]) {
;     f32x4 q[2][4];
; #pragma unroll
;     for (int ai = 0; ai < 2; ++ai)
; #pragma unroll
;         for (int m = 0; m < 4; ++m) q[ai][m] = *(const f32x4*)(SS + (size_t)(row0 + ai * HALF + m * 16) * 16 + 4 * fq);
; #pragma unroll
;     for (int ai = 0; ai < 2; ++ai)
; #pragma unroll
;         for (int m = 0; m < 4; ++m) { float t = (q[ai][m][0] + q[ai][m][1]) + (q[ai][m][2] + q[ai][m][3]); t += __shfl_xor(t, 16); t += __shfl_xor(t, 32); rsv[ai][m] = __builtin_amdgcn_rsqf(t * (1.0f / 1024.0f) + 1e-6f); }
; }
;     __device__ __forceinline__ void operator()(const f32x4 (&acc)[2][2][4][2], const Unit& u, int wr, int wc, int fr, int fq) const {
;         const int row0 = u.pm * BM + wr * 64 + fr, col0 = u.pn * BM + wc * 32 + 8 * fq;
;         float rsv[2][4]; row_rs8(SS, row0, fq, rsv);
; #pragma unroll
;         for (int ai = 0; ai < 2; ++ai)
; #pragma unroll
;             for (int mp = 0; mp < 2; ++mp) {
;                 u32x4 xr[2][2], pr[2][2];
; #pragma unroll
;                 for (int mm = 0; mm < 2; ++mm)
; #pragma unroll
;                     for (int bj = 0; bj < 2; ++bj) { const size_t off = (size_t)(row0 + ai * HALF + (2 * mp + mm) * 16) * 1024 + col0 + bj * HALF; xr[mm][bj] = *(const u32x4*)(XB + off); pr[mm][bj] = *(const u32x4*)(P + off); }
.LBB0_1256:
	v_mbcnt_lo_u32_b32 v247, -1, 0
	v_mbcnt_hi_u32_b32 v247, -1, v247
	v_and_b32_e32 v247, 32, v247
	v_lshrrev_b32_e32 v247, 1, v247
	v_mul_u32_u24_e32 v247, 3, v247
	v_lshl_add_u32 v219, s51, 8, v193
	v_or_b32_e32 v228, 16, v219
	v_or_b32_e32 v229, 32, v219
	v_or_b32_e32 v230, 48, v219
	v_add_u32_e32 v231, 0x80, v219
	v_add_u32_e32 v232, 0x90, v219
	v_add_u32_e32 v233, 0xa0, v219
	v_add_u32_e32 v234, 0xb0, v219
	v_mov_b32_e32 v227, 0
	v_lshlrev_b32_e32 v226, 6, v219
	v_lshl_add_u64 v[220:221], v[184:185], 0, v[226:227]
	global_load_dwordx4 v[124:127], v[220:221], off
	v_lshlrev_b32_e32 v226, 6, v228
	v_lshl_add_u64 v[220:221], v[184:185], 0, v[226:227]
	global_load_dwordx4 v[132:135], v[220:221], off
	v_lshlrev_b32_e32 v226, 6, v229
	v_lshl_add_u64 v[220:221], v[184:185], 0, v[226:227]
	global_load_dwordx4 v[136:139], v[220:221], off
	v_lshlrev_b32_e32 v226, 6, v230
	v_lshl_add_u64 v[220:221], v[184:185], 0, v[226:227]
	global_load_dwordx4 v[140:143], v[220:221], off
	v_lshlrev_b32_e32 v226, 6, v231
	v_lshl_add_u64 v[220:221], v[184:185], 0, v[226:227]
	global_load_dwordx4 v[144:147], v[220:221], off
	v_lshlrev_b32_e32 v226, 6, v232
	v_lshl_add_u64 v[220:221], v[184:185], 0, v[226:227]
	global_load_dwordx4 v[148:151], v[220:221], off
	v_lshlrev_b32_e32 v226, 6, v233
	v_lshl_add_u64 v[220:221], v[184:185], 0, v[226:227]
	global_load_dwordx4 v[152:155], v[220:221], off
	v_lshlrev_b32_e32 v226, 6, v234
	v_lshl_add_u64 v[220:221], v[184:185], 0, v[226:227]
	global_load_dwordx4 v[156:159], v[220:221], off
	v_lshl_or_b32 v246, s52, 8, v213
	v_lshlrev_b32_e32 v246, 1, v246
	v_lshl_add_u32 v219, v219, 11, v246
	v_lshl_add_u32 v228, v228, 11, v246
	v_lshl_add_u32 v229, v229, 11, v246
	v_lshl_add_u32 v230, v230, 11, v246
	v_lshl_add_u32 v231, v231, 11, v246
	v_lshl_add_u32 v232, v232, 11, v246
	v_lshl_add_u32 v233, v233, 11, v246
	v_lshl_add_u32 v234, v234, 11, v246
	v_xor_b32_e32 v243, 16, v217
	v_xor_b32_e32 v244, 32, v217
	v_lshlrev_b32_e32 v243, 2, v243
	v_lshlrev_b32_e32 v244, 2, v244
	global_load_dwordx4 v[160:163], v219, s[34:35]
	global_load_dwordx4 v[164:167], v219, s[46:47]
	global_load_dwordx4 v[168:171], v219, s[34:35] offset:256
	global_load_dwordx4 v[172:175], v219, s[46:47] offset:256
	global_load_dwordx4 v[196:199], v228, s[34:35]
	global_load_dwordx4 v[200:203], v228, s[46:47]
	global_load_dwordx4 v[204:207], v228, s[34:35] offset:256
	global_load_dwordx4 v[208:211], v228, s[46:47] offset:256
	s_waitcnt vmcnt(8)
	v_pk_add_f32 v[124:125], v[124:125], v[126:127]
	v_pk_add_f32 v[132:133], v[132:133], v[134:135]
	v_pk_add_f32 v[136:137], v[136:137], v[138:139]
	v_pk_add_f32 v[140:141], v[140:141], v[142:143]
	v_pk_add_f32 v[144:145], v[144:145], v[146:147]
	v_pk_add_f32 v[148:149], v[148:149], v[150:151]
	v_pk_add_f32 v[152:153], v[152:153], v[154:155]
	v_pk_add_f32 v[156:157], v[156:157], v[158:159]
	v_add_f32_e32 v235, v124, v125
	v_add_f32_e32 v236, v132, v133
	v_add_f32_e32 v237, v136, v137
	v_add_f32_e32 v238, v140, v141
	v_add_f32_e32 v239, v144, v145
	v_add_f32_e32 v240, v148, v149
	v_add_f32_e32 v241, v152, v153
	v_add_f32_e32 v242, v156, v157
	ds_bpermute_b32 v126, v243, v235
	ds_bpermute_b32 v134, v243, v236
	ds_bpermute_b32 v138, v243, v237
	ds_bpermute_b32 v142, v243, v238
	ds_bpermute_b32 v146, v243, v239
	ds_bpermute_b32 v150, v243, v240
	ds_bpermute_b32 v154, v243, v241
	ds_bpermute_b32 v158, v243, v242
	s_waitcnt lgkmcnt(7)
	v_add_f32_e32 v235, v235, v126
	s_waitcnt lgkmcnt(6)
	v_add_f32_e32 v236, v236, v134
	s_waitcnt lgkmcnt(5)
	v_add_f32_e32 v237, v237, v138
	s_waitcnt lgkmcnt(4)
	v_add_f32_e32 v238, v238, v142
	s_waitcnt lgkmcnt(3)
	v_add_f32_e32 v239, v239, v146
	s_waitcnt lgkmcnt(2)
	v_add_f32_e32 v240, v240, v150
	s_waitcnt lgkmcnt(1)
	v_add_f32_e32 v241, v241, v154
	s_waitcnt lgkmcnt(0)
	v_add_f32_e32 v242, v242, v158
	ds_bpermute_b32 v126, v244, v235
	ds_bpermute_b32 v134, v244, v236
	ds_bpermute_b32 v138, v244, v237
	ds_bpermute_b32 v142, v244, v238
	ds_bpermute_b32 v146, v244, v239
	ds_bpermute_b32 v150, v244, v240
	ds_bpermute_b32 v154, v244, v241
	ds_bpermute_b32 v158, v244, v242
	s_waitcnt lgkmcnt(7)
	v_add_f32_e32 v235, v235, v126
	s_waitcnt lgkmcnt(6)
	v_add_f32_e32 v236, v236, v134
	s_waitcnt lgkmcnt(5)
	v_add_f32_e32 v237, v237, v138
	s_waitcnt lgkmcnt(4)
	v_add_f32_e32 v238, v238, v142
	s_waitcnt lgkmcnt(3)
	v_add_f32_e32 v239, v239, v146
	s_waitcnt lgkmcnt(2)
	v_add_f32_e32 v240, v240, v150
	s_waitcnt lgkmcnt(1)
	v_add_f32_e32 v241, v241, v154
	s_waitcnt lgkmcnt(0)
; __device__ __forceinline__ float fast_rcp(float x) { return __builtin_amdgcn_rcpf(x); }
; __device__ __forceinline__ void row_rs8(const float* SS, int row0, int fq, float (&rsv)[2][4]) {
;     ...
;         for (int m = 0; m < 4; ++m) q[ai][m] = *(const f32x4*)(SS + (size_t)(row0 + ai * HALF + m * 16) * 16 + 4 * fq);
; #pragma unroll
;     for (int ai = 0; ai < 2; ++ai)
; #pragma unroll
;         for (int m = 0; m < 4; ++m) { float t = (q[ai][m][0] + q[ai][m][1]) + (q[ai][m][2] + q[ai][m][3]); t += __shfl_xor(t, 16); t += __shfl_xor(t, 32); rsv[ai][m] = __builtin_amdgcn_rsqf(t * (1.0f / 1024.0f) + 1e-6f); }
;     __device__ __forceinline__ void operator()(const f32x4 (&acc)[2][2][4][2], const Unit& u, int wr, int wc, int fr, int fq) const {
;     ...
;                 for (int mm = 0; mm < 2; ++mm) {
;                     const int m = 2 * mp + mm; const int r = row0 + ai * HALF + m * 16; const float nrs = rsv[ai][m] * -1.4426950408889634f;
; #pragma unroll
;                     for (int bj = 0; bj < 2; ++bj) {
;                         const size_t off = (size_t)r * 1024 + col0 + bj * HALF;
;                         const unsigned xw[4] = {xr[mm][bj].x, xr[mm][bj].y, xr[mm][bj].z, xr[mm][bj].w}, pw[4] = {pr[mm][bj].x, pr[mm][bj].y, pr[mm][bj].z, pr[mm][bj].w};
;                         f32x4 o[2];
; #pragma unroll
;                         for (int q = 0; q < 4; ++q) {
;                             const float t0 = acc[ai][bj][m][q >> 1][2 * (q & 1)] * nrs, t1 = acc[ai][bj][m][q >> 1][2 * (q & 1) + 1] * nrs;
;                             o[q >> 1][2 * (q & 1)] = __uint_as_float(xw[q] << 16) + fast_rcp(1.0f + __builtin_amdgcn_exp2f(t0)) * __uint_as_float(pw[q] << 16);
;                             o[q >> 1][2 * (q & 1) + 1] = __uint_as_float(xw[q] & 0xffff0000u) + fast_rcp(1.0f + __builtin_amdgcn_exp2f(t1)) * __uint_as_float(pw[q] & 0xffff0000u);
;                         }
;                         *(f32x4*)(Y + off) = o[0]; *(f32x4*)(Y + off + 4) = o[1];
	v_add_f32_e32 v242, v242, v158
	v_fmamk_f32 v235, v235, 0x3a800000, v218
	v_fmamk_f32 v236, v236, 0x3a800000, v218
	v_fmamk_f32 v237, v237, 0x3a800000, v218
	v_fmamk_f32 v238, v238, 0x3a800000, v218
	v_fmamk_f32 v239, v239, 0x3a800000, v218
	v_fmamk_f32 v240, v240, 0x3a800000, v218
	v_fmamk_f32 v241, v241, 0x3a800000, v218
	v_fmamk_f32 v242, v242, 0x3a800000, v218
	v_rsq_f32_e32 v235, v235
	v_rsq_f32_e32 v236, v236
	v_rsq_f32_e32 v237, v237
	v_rsq_f32_e32 v238, v238
	v_rsq_f32_e32 v239, v239
	v_rsq_f32_e32 v240, v240
	v_rsq_f32_e32 v241, v241
	v_rsq_f32_e32 v242, v242
	global_load_dwordx4 v[124:127], v229, s[34:35]
	global_load_dwordx4 v[132:135], v229, s[46:47]
	global_load_dwordx4 v[136:139], v229, s[34:35] offset:256
	global_load_dwordx4 v[140:143], v229, s[46:47] offset:256
	global_load_dwordx4 v[144:147], v230, s[34:35]
	global_load_dwordx4 v[148:151], v230, s[46:47]
	global_load_dwordx4 v[152:155], v230, s[34:35] offset:256
	global_load_dwordx4 v[156:159], v230, s[46:47] offset:256
	v_mul_f32_e32 v235, 0xbfb8aa3b, v235
	v_mul_f32_e32 v236, 0xbfb8aa3b, v236
	v_mul_f32_e32 v237, 0xbfb8aa3b, v237
	v_mul_f32_e32 v238, 0xbfb8aa3b, v238
	v_mul_f32_e32 v239, 0xbfb8aa3b, v239
	v_mul_f32_e32 v240, 0xbfb8aa3b, v240
	v_mul_f32_e32 v241, 0xbfb8aa3b, v241
	v_mul_f32_e32 v242, 0xbfb8aa3b, v242
	v_mov_b32_e32 v224, v235
	v_pk_mul_f32 v[128:129], v[128:129], v[224:225] op_sel_hi:[1,0]
	v_pk_mul_f32 v[130:131], v[130:131], v[224:225] op_sel_hi:[1,0]
	v_pk_mul_f32 v[120:121], v[120:121], v[224:225] op_sel_hi:[1,0]
	v_pk_mul_f32 v[122:123], v[122:123], v[224:225] op_sel_hi:[1,0]
	v_exp_f32_e32 v128, v128
	v_exp_f32_e32 v129, v129
	v_exp_f32_e32 v130, v130
	v_exp_f32_e32 v131, v131
	v_exp_f32_e32 v120, v120
	v_exp_f32_e32 v121, v121
	v_exp_f32_e32 v122, v122
	v_exp_f32_e32 v123, v123
	v_pk_add_f32 v[128:129], v[128:129], 1.0 op_sel_hi:[1,0]
	v_pk_add_f32 v[130:131], v[130:131], 1.0 op_sel_hi:[1,0]
	v_pk_add_f32 v[120:121], v[120:121], 1.0 op_sel_hi:[1,0]
	v_pk_add_f32 v[122:123], v[122:123], 1.0 op_sel_hi:[1,0]
	v_rcp_f32_e32 v128, v128
	v_rcp_f32_e32 v129, v129
	v_rcp_f32_e32 v130, v130
	v_rcp_f32_e32 v131, v131
	v_rcp_f32_e32 v120, v120
	v_rcp_f32_e32 v121, v121
	v_rcp_f32_e32 v122, v122
	v_rcp_f32_e32 v123, v123
	v_lshlrev_b32_e32 v245, 1, v219
	v_sub_u32_e32 v245, v245, v247
	s_waitcnt vmcnt(14)
	v_lshlrev_b32_e32 v220, 16, v160
	v_and_b32_e32 v221, 0xffff0000, v160
	v_lshlrev_b32_e32 v222, 16, v164
	v_and_b32_e32 v223, 0xffff0000, v164
	v_pk_fma_f32 v[128:129], v[128:129], v[222:223], v[220:221]
	v_lshlrev_b32_e32 v220, 16, v161
	v_and_b32_e32 v221, 0xffff0000, v161
	v_lshlrev_b32_e32 v222, 16, v165
	v_and_b32_e32 v223, 0xffff0000, v165
	v_pk_fma_f32 v[130:131], v[130:131], v[222:223], v[220:221]
	v_lshlrev_b32_e32 v220, 16, v162
	v_and_b32_e32 v221, 0xffff0000, v162
	v_lshlrev_b32_e32 v222, 16, v166
	v_and_b32_e32 v223, 0xffff0000, v166
	v_pk_fma_f32 v[120:121], v[120:121], v[222:223], v[220:221]
	v_lshlrev_b32_e32 v220, 16, v163
	v_and_b32_e32 v221, 0xffff0000, v163
	v_lshlrev_b32_e32 v222, 16, v167
	v_and_b32_e32 v223, 0xffff0000, v167
	v_pk_fma_f32 v[122:123], v[122:123], v[222:223], v[220:221]
	s_nop 1
	v_permlane32_swap_b32_e32 v128, v120
	v_permlane32_swap_b32_e32 v129, v121
	v_permlane32_swap_b32_e32 v130, v122
	v_permlane32_swap_b32_e32 v131, v123
	global_store_dwordx4 v245, v[128:131], s[24:25]
	global_store_dwordx4 v245, v[120:123], s[24:25] offset:64
	global_load_dwordx4 v[160:163], v231, s[34:35]
	global_load_dwordx4 v[164:167], v231, s[46:47]
	v_mov_b32_e32 v224, v235
	v_pk_mul_f32 v[116:117], v[116:117], v[224:225] op_sel_hi:[1,0]
	v_pk_mul_f32 v[118:119], v[118:119], v[224:225] op_sel_hi:[1,0]
	v_pk_mul_f32 v[112:113], v[112:113], v[224:225] op_sel_hi:[1,0]
	v_pk_mul_f32 v[114:115], v[114:115], v[224:225] op_sel_hi:[1,0]
	v_exp_f32_e32 v116, v116
	v_exp_f32_e32 v117, v117
	v_exp_f32_e32 v118, v118
	v_exp_f32_e32 v119, v119
	v_exp_f32_e32 v112, v112
	v_exp_f32_e32 v113, v113
	v_exp_f32_e32 v114, v114
	v_exp_f32_e32 v115, v115
	v_pk_add_f32 v[116:117], v[116:117], 1.0 op_sel_hi:[1,0]
	v_pk_add_f32 v[118:119], v[118:119], 1.0 op_sel_hi:[1,0]
	v_pk_add_f32 v[112:113], v[112:113], 1.0 op_sel_hi:[1,0]
	v_pk_add_f32 v[114:115], v[114:115], 1.0 op_sel_hi:[1,0]
	v_rcp_f32_e32 v116, v116
	v_rcp_f32_e32 v117, v117
	v_rcp_f32_e32 v118, v118
	v_rcp_f32_e32 v119, v119
	v_rcp_f32_e32 v112, v112
	v_rcp_f32_e32 v113, v113
	v_rcp_f32_e32 v114, v114
	v_rcp_f32_e32 v115, v115
	v_lshlrev_b32_e32 v245, 1, v219
	v_sub_u32_e32 v245, v245, v247
	s_waitcnt vmcnt(16)
; __device__ __forceinline__ float fast_rcp(float x) { return __builtin_amdgcn_rcpf(x); }
;     __device__ __forceinline__ void operator()(const f32x4 (&acc)[2][2][4][2], const Unit& u, int wr, int wc, int fr, int fq) const {
;     ...
;                 for (int mm = 0; mm < 2; ++mm) {
;                     const int m = 2 * mp + mm; const int r = row0 + ai * HALF + m * 16; const float nrs = rsv[ai][m] * -1.4426950408889634f;
; #pragma unroll
;                     for (int bj = 0; bj < 2; ++bj) {
;                         const size_t off = (size_t)r * 1024 + col0 + bj * HALF;
;                         const unsigned xw[4] = {xr[mm][bj].x, xr[mm][bj].y, xr[mm][bj].z, xr[mm][bj].w}, pw[4] = {pr[mm][bj].x, pr[mm][bj].y, pr[mm][bj].z, pr[mm][bj].w};
;                         f32x4 o[2];
; #pragma unroll
;                         for (int q = 0; q < 4; ++q) {
;                             const float t0 = acc[ai][bj][m][q >> 1][2 * (q & 1)] * nrs, t1 = acc[ai][bj][m][q >> 1][2 * (q & 1) + 1] * nrs;
;                             o[q >> 1][2 * (q & 1)] = __uint_as_float(xw[q] << 16) + fast_rcp(1.0f + __builtin_amdgcn_exp2f(t0)) * __uint_as_float(pw[q] << 16);
;                             o[q >> 1][2 * (q & 1) + 1] = __uint_as_float(xw[q] & 0xffff0000u) + fast_rcp(1.0f + __builtin_amdgcn_exp2f(t1)) * __uint_as_float(pw[q] & 0xffff0000u);
;                         }
;                         *(f32x4*)(Y + off) = o[0]; *(f32x4*)(Y + off + 4) = o[1];
	v_lshlrev_b32_e32 v220, 16, v168
	v_and_b32_e32 v221, 0xffff0000, v168
	v_lshlrev_b32_e32 v222, 16, v172
	v_and_b32_e32 v223, 0xffff0000, v172
	v_pk_fma_f32 v[116:117], v[116:117], v[222:223], v[220:221]
	v_lshlrev_b32_e32 v220, 16, v169
	v_and_b32_e32 v221, 0xffff0000, v169
	v_lshlrev_b32_e32 v222, 16, v173
	v_and_b32_e32 v223, 0xffff0000, v173
	v_pk_fma_f32 v[118:119], v[118:119], v[222:223], v[220:221]
	v_lshlrev_b32_e32 v220, 16, v170
	v_and_b32_e32 v221, 0xffff0000, v170
	v_lshlrev_b32_e32 v222, 16, v174
	v_and_b32_e32 v223, 0xffff0000, v174
	v_pk_fma_f32 v[112:113], v[112:113], v[222:223], v[220:221]
	v_lshlrev_b32_e32 v220, 16, v171
	v_and_b32_e32 v221, 0xffff0000, v171
	v_lshlrev_b32_e32 v222, 16, v175
	v_and_b32_e32 v223, 0xffff0000, v175
	v_pk_fma_f32 v[114:115], v[114:115], v[222:223], v[220:221]
	s_nop 1
	v_permlane32_swap_b32_e32 v116, v112
	v_permlane32_swap_b32_e32 v117, v113
	v_permlane32_swap_b32_e32 v118, v114
	v_permlane32_swap_b32_e32 v119, v115
	global_store_dwordx4 v245, v[116:119], s[24:25] offset:512
	global_store_dwordx4 v245, v[112:115], s[24:25] offset:576
	global_load_dwordx4 v[168:171], v231, s[34:35] offset:256
	global_load_dwordx4 v[172:175], v231, s[46:47] offset:256
	v_mov_b32_e32 v224, v236
	v_pk_mul_f32 v[108:109], v[108:109], v[224:225] op_sel_hi:[1,0]
	v_pk_mul_f32 v[110:111], v[110:111], v[224:225] op_sel_hi:[1,0]
	v_pk_mul_f32 v[104:105], v[104:105], v[224:225] op_sel_hi:[1,0]
	v_pk_mul_f32 v[106:107], v[106:107], v[224:225] op_sel_hi:[1,0]
	v_exp_f32_e32 v108, v108
	v_exp_f32_e32 v109, v109
	v_exp_f32_e32 v110, v110
	v_exp_f32_e32 v111, v111
	v_exp_f32_e32 v104, v104
	v_exp_f32_e32 v105, v105
	v_exp_f32_e32 v106, v106
	v_exp_f32_e32 v107, v107
	v_pk_add_f32 v[108:109], v[108:109], 1.0 op_sel_hi:[1,0]
	v_pk_add_f32 v[110:111], v[110:111], 1.0 op_sel_hi:[1,0]
	v_pk_add_f32 v[104:105], v[104:105], 1.0 op_sel_hi:[1,0]
	v_pk_add_f32 v[106:107], v[106:107], 1.0 op_sel_hi:[1,0]
	v_rcp_f32_e32 v108, v108
	v_rcp_f32_e32 v109, v109
	v_rcp_f32_e32 v110, v110
	v_rcp_f32_e32 v111, v111
	v_rcp_f32_e32 v104, v104
	v_rcp_f32_e32 v105, v105
	v_rcp_f32_e32 v106, v106
	v_rcp_f32_e32 v107, v107
	v_lshlrev_b32_e32 v245, 1, v228
	v_sub_u32_e32 v245, v245, v247
	s_waitcnt vmcnt(18)
	v_lshlrev_b32_e32 v220, 16, v196
	v_and_b32_e32 v221, 0xffff0000, v196
	v_lshlrev_b32_e32 v222, 16, v200
	v_and_b32_e32 v223, 0xffff0000, v200
	v_pk_fma_f32 v[108:109], v[108:109], v[222:223], v[220:221]
	v_lshlrev_b32_e32 v220, 16, v197
	v_and_b32_e32 v221, 0xffff0000, v197
	v_lshlrev_b32_e32 v222, 16, v201
	v_and_b32_e32 v223, 0xffff0000, v201
	v_pk_fma_f32 v[110:111], v[110:111], v[222:223], v[220:221]
	v_lshlrev_b32_e32 v220, 16, v198
	v_and_b32_e32 v221, 0xffff0000, v198
	v_lshlrev_b32_e32 v222, 16, v202
	v_and_b32_e32 v223, 0xffff0000, v202
	v_pk_fma_f32 v[104:105], v[104:105], v[222:223], v[220:221]
	v_lshlrev_b32_e32 v220, 16, v199
	v_and_b32_e32 v221, 0xffff0000, v199
	v_lshlrev_b32_e32 v222, 16, v203
	v_and_b32_e32 v223, 0xffff0000, v203
	v_pk_fma_f32 v[106:107], v[106:107], v[222:223], v[220:221]
	s_nop 1
	v_permlane32_swap_b32_e32 v108, v104
	v_permlane32_swap_b32_e32 v109, v105
	v_permlane32_swap_b32_e32 v110, v106
	v_permlane32_swap_b32_e32 v111, v107
	global_store_dwordx4 v245, v[108:111], s[24:25]
	global_store_dwordx4 v245, v[104:107], s[24:25] offset:64
	global_load_dwordx4 v[196:199], v232, s[34:35]
	global_load_dwordx4 v[200:203], v232, s[46:47]
	v_mov_b32_e32 v224, v236
	v_pk_mul_f32 v[100:101], v[100:101], v[224:225] op_sel_hi:[1,0]
	v_pk_mul_f32 v[102:103], v[102:103], v[224:225] op_sel_hi:[1,0]
	v_pk_mul_f32 v[96:97], v[96:97], v[224:225] op_sel_hi:[1,0]
	v_pk_mul_f32 v[98:99], v[98:99], v[224:225] op_sel_hi:[1,0]
	v_exp_f32_e32 v100, v100
	v_exp_f32_e32 v101, v101
	v_exp_f32_e32 v102, v102
	v_exp_f32_e32 v103, v103
	v_exp_f32_e32 v96, v96
	v_exp_f32_e32 v97, v97
	v_exp_f32_e32 v98, v98
	v_exp_f32_e32 v99, v99
	v_pk_add_f32 v[100:101], v[100:101], 1.0 op_sel_hi:[1,0]
	v_pk_add_f32 v[102:103], v[102:103], 1.0 op_sel_hi:[1,0]
	v_pk_add_f32 v[96:97], v[96:97], 1.0 op_sel_hi:[1,0]
	v_pk_add_f32 v[98:99], v[98:99], 1.0 op_sel_hi:[1,0]
	v_rcp_f32_e32 v100, v100
	v_rcp_f32_e32 v101, v101
	v_rcp_f32_e32 v102, v102
	v_rcp_f32_e32 v103, v103
	v_rcp_f32_e32 v96, v96
	v_rcp_f32_e32 v97, v97
	v_rcp_f32_e32 v98, v98
	v_rcp_f32_e32 v99, v99
	v_lshlrev_b32_e32 v245, 1, v228
	v_sub_u32_e32 v245, v245, v247
	s_waitcnt vmcnt(20)
	v_lshlrev_b32_e32 v220, 16, v204
	v_and_b32_e32 v221, 0xffff0000, v204
	v_lshlrev_b32_e32 v222, 16, v208
	v_and_b32_e32 v223, 0xffff0000, v208
	v_pk_fma_f32 v[100:101], v[100:101], v[222:223], v[220:221]
	v_lshlrev_b32_e32 v220, 16, v205
	v_and_b32_e32 v221, 0xffff0000, v205
	v_lshlrev_b32_e32 v222, 16, v209
	v_and_b32_e32 v223, 0xffff0000, v209
	v_pk_fma_f32 v[102:103], v[102:103], v[222:223], v[220:221]
	v_lshlrev_b32_e32 v220, 16, v206
	v_and_b32_e32 v221, 0xffff0000, v206
	v_lshlrev_b32_e32 v222, 16, v210
	v_and_b32_e32 v223, 0xffff0000, v210
	v_pk_fma_f32 v[96:97], v[96:97], v[222:223], v[220:221]
	v_lshlrev_b32_e32 v220, 16, v207
	v_and_b32_e32 v221, 0xffff0000, v207
	v_lshlrev_b32_e32 v222, 16, v211
	v_and_b32_e32 v223, 0xffff0000, v211
	v_pk_fma_f32 v[98:99], v[98:99], v[222:223], v[220:221]
	s_nop 1
	v_permlane32_swap_b32_e32 v100, v96
	v_permlane32_swap_b32_e32 v101, v97
	v_permlane32_swap_b32_e32 v102, v98
	v_permlane32_swap_b32_e32 v103, v99
	global_store_dwordx4 v245, v[100:103], s[24:25] offset:512
	global_store_dwordx4 v245, v[96:99], s[24:25] offset:576
	global_load_dwordx4 v[204:207], v232, s[34:35] offset:256
	global_load_dwordx4 v[208:211], v232, s[46:47] offset:256
	v_mov_b32_e32 v224, v237
	v_pk_mul_f32 v[92:93], v[92:93], v[224:225] op_sel_hi:[1,0]
	v_pk_mul_f32 v[94:95], v[94:95], v[224:225] op_sel_hi:[1,0]
	v_pk_mul_f32 v[88:89], v[88:89], v[224:225] op_sel_hi:[1,0]
	v_pk_mul_f32 v[90:91], v[90:91], v[224:225] op_sel_hi:[1,0]
	v_exp_f32_e32 v92, v92
	v_exp_f32_e32 v93, v93
	v_exp_f32_e32 v94, v94
	v_exp_f32_e32 v95, v95
	v_exp_f32_e32 v88, v88
	v_exp_f32_e32 v89, v89
	v_exp_f32_e32 v90, v90
	v_exp_f32_e32 v91, v91
	v_pk_add_f32 v[92:93], v[92:93], 1.0 op_sel_hi:[1,0]
	v_pk_add_f32 v[94:95], v[94:95], 1.0 op_sel_hi:[1,0]
	v_pk_add_f32 v[88:89], v[88:89], 1.0 op_sel_hi:[1,0]
	v_pk_add_f32 v[90:91], v[90:91], 1.0 op_sel_hi:[1,0]
	v_rcp_f32_e32 v92, v92
	v_rcp_f32_e32 v93, v93
	v_rcp_f32_e32 v94, v94
	v_rcp_f32_e32 v95, v95
	v_rcp_f32_e32 v88, v88
	v_rcp_f32_e32 v89, v89
	v_rcp_f32_e32 v90, v90
	v_rcp_f32_e32 v91, v91
	v_lshlrev_b32_e32 v245, 1, v229
	v_sub_u32_e32 v245, v245, v247
	s_waitcnt vmcnt(22)
; __device__ __forceinline__ float fast_rcp(float x) { return __builtin_amdgcn_rcpf(x); }
;     __device__ __forceinline__ void operator()(const f32x4 (&acc)[2][2][4][2], const Unit& u, int wr, int wc, int fr, int fq) const {
;     ...
;                 for (int mm = 0; mm < 2; ++mm) {
;                     const int m = 2 * mp + mm; const int r = row0 + ai * HALF + m * 16; const float nrs = rsv[ai][m] * -1.4426950408889634f;
; #pragma unroll
;                     for (int bj = 0; bj < 2; ++bj) {
;                         const size_t off = (size_t)r * 1024 + col0 + bj * HALF;
;                         const unsigned xw[4] = {xr[mm][bj].x, xr[mm][bj].y, xr[mm][bj].z, xr[mm][bj].w}, pw[4] = {pr[mm][bj].x, pr[mm][bj].y, pr[mm][bj].z, pr[mm][bj].w};
;                         f32x4 o[2];
; #pragma unroll
;                         for (int q = 0; q < 4; ++q) {
;                             const float t0 = acc[ai][bj][m][q >> 1][2 * (q & 1)] * nrs, t1 = acc[ai][bj][m][q >> 1][2 * (q & 1) + 1] * nrs;
;                             o[q >> 1][2 * (q & 1)] = __uint_as_float(xw[q] << 16) + fast_rcp(1.0f + __builtin_amdgcn_exp2f(t0)) * __uint_as_float(pw[q] << 16);
;                             o[q >> 1][2 * (q & 1) + 1] = __uint_as_float(xw[q] & 0xffff0000u) + fast_rcp(1.0f + __builtin_amdgcn_exp2f(t1)) * __uint_as_float(pw[q] & 0xffff0000u);
;                         }
;                         *(f32x4*)(Y + off) = o[0]; *(f32x4*)(Y + off + 4) = o[1];
	v_lshlrev_b32_e32 v220, 16, v124
	v_and_b32_e32 v221, 0xffff0000, v124
	v_lshlrev_b32_e32 v222, 16, v132
	v_and_b32_e32 v223, 0xffff0000, v132
	v_pk_fma_f32 v[92:93], v[92:93], v[222:223], v[220:221]
	v_lshlrev_b32_e32 v220, 16, v125
	v_and_b32_e32 v221, 0xffff0000, v125
	v_lshlrev_b32_e32 v222, 16, v133
	v_and_b32_e32 v223, 0xffff0000, v133
	v_pk_fma_f32 v[94:95], v[94:95], v[222:223], v[220:221]
	v_lshlrev_b32_e32 v220, 16, v126
	v_and_b32_e32 v221, 0xffff0000, v126
	v_lshlrev_b32_e32 v222, 16, v134
	v_and_b32_e32 v223, 0xffff0000, v134
	v_pk_fma_f32 v[88:89], v[88:89], v[222:223], v[220:221]
	v_lshlrev_b32_e32 v220, 16, v127
	v_and_b32_e32 v221, 0xffff0000, v127
	v_lshlrev_b32_e32 v222, 16, v135
	v_and_b32_e32 v223, 0xffff0000, v135
	v_pk_fma_f32 v[90:91], v[90:91], v[222:223], v[220:221]
	s_nop 1
	v_permlane32_swap_b32_e32 v92, v88
	v_permlane32_swap_b32_e32 v93, v89
	v_permlane32_swap_b32_e32 v94, v90
	v_permlane32_swap_b32_e32 v95, v91
	global_store_dwordx4 v245, v[92:95], s[24:25]
	global_store_dwordx4 v245, v[88:91], s[24:25] offset:64
	global_load_dwordx4 v[124:127], v233, s[34:35]
	global_load_dwordx4 v[132:135], v233, s[46:47]
	v_mov_b32_e32 v224, v237
	v_pk_mul_f32 v[84:85], v[84:85], v[224:225] op_sel_hi:[1,0]
	v_pk_mul_f32 v[86:87], v[86:87], v[224:225] op_sel_hi:[1,0]
	v_pk_mul_f32 v[80:81], v[80:81], v[224:225] op_sel_hi:[1,0]
	v_pk_mul_f32 v[82:83], v[82:83], v[224:225] op_sel_hi:[1,0]
	v_exp_f32_e32 v84, v84
	v_exp_f32_e32 v85, v85
	v_exp_f32_e32 v86, v86
	v_exp_f32_e32 v87, v87
	v_exp_f32_e32 v80, v80
	v_exp_f32_e32 v81, v81
	v_exp_f32_e32 v82, v82
	v_exp_f32_e32 v83, v83
	v_pk_add_f32 v[84:85], v[84:85], 1.0 op_sel_hi:[1,0]
	v_pk_add_f32 v[86:87], v[86:87], 1.0 op_sel_hi:[1,0]
	v_pk_add_f32 v[80:81], v[80:81], 1.0 op_sel_hi:[1,0]
	v_pk_add_f32 v[82:83], v[82:83], 1.0 op_sel_hi:[1,0]
	v_rcp_f32_e32 v84, v84
	v_rcp_f32_e32 v85, v85
	v_rcp_f32_e32 v86, v86
	v_rcp_f32_e32 v87, v87
	v_rcp_f32_e32 v80, v80
	v_rcp_f32_e32 v81, v81
	v_rcp_f32_e32 v82, v82
	v_rcp_f32_e32 v83, v83
	v_lshlrev_b32_e32 v245, 1, v229
	v_sub_u32_e32 v245, v245, v247
	s_waitcnt vmcnt(24)
	v_lshlrev_b32_e32 v220, 16, v136
	v_and_b32_e32 v221, 0xffff0000, v136
	v_lshlrev_b32_e32 v222, 16, v140
	v_and_b32_e32 v223, 0xffff0000, v140
	v_pk_fma_f32 v[84:85], v[84:85], v[222:223], v[220:221]
	v_lshlrev_b32_e32 v220, 16, v137
	v_and_b32_e32 v221, 0xffff0000, v137
	v_lshlrev_b32_e32 v222, 16, v141
	v_and_b32_e32 v223, 0xffff0000, v141
	v_pk_fma_f32 v[86:87], v[86:87], v[222:223], v[220:221]
	v_lshlrev_b32_e32 v220, 16, v138
	v_and_b32_e32 v221, 0xffff0000, v138
	v_lshlrev_b32_e32 v222, 16, v142
	v_and_b32_e32 v223, 0xffff0000, v142
	v_pk_fma_f32 v[80:81], v[80:81], v[222:223], v[220:221]
	v_lshlrev_b32_e32 v220, 16, v139
	v_and_b32_e32 v221, 0xffff0000, v139
	v_lshlrev_b32_e32 v222, 16, v143
	v_and_b32_e32 v223, 0xffff0000, v143
	v_pk_fma_f32 v[82:83], v[82:83], v[222:223], v[220:221]
	s_nop 1
	v_permlane32_swap_b32_e32 v84, v80
	v_permlane32_swap_b32_e32 v85, v81
	v_permlane32_swap_b32_e32 v86, v82
	v_permlane32_swap_b32_e32 v87, v83
	global_store_dwordx4 v245, v[84:87], s[24:25] offset:512
	global_store_dwordx4 v245, v[80:83], s[24:25] offset:576
	global_load_dwordx4 v[136:139], v233, s[34:35] offset:256
	global_load_dwordx4 v[140:143], v233, s[46:47] offset:256
	v_mov_b32_e32 v224, v238
	v_pk_mul_f32 v[76:77], v[76:77], v[224:225] op_sel_hi:[1,0]
	v_pk_mul_f32 v[78:79], v[78:79], v[224:225] op_sel_hi:[1,0]
	v_pk_mul_f32 v[72:73], v[72:73], v[224:225] op_sel_hi:[1,0]
	v_pk_mul_f32 v[74:75], v[74:75], v[224:225] op_sel_hi:[1,0]
	v_exp_f32_e32 v76, v76
	v_exp_f32_e32 v77, v77
	v_exp_f32_e32 v78, v78
	v_exp_f32_e32 v79, v79
	v_exp_f32_e32 v72, v72
	v_exp_f32_e32 v73, v73
	v_exp_f32_e32 v74, v74
	v_exp_f32_e32 v75, v75
	v_pk_add_f32 v[76:77], v[76:77], 1.0 op_sel_hi:[1,0]
	v_pk_add_f32 v[78:79], v[78:79], 1.0 op_sel_hi:[1,0]
	v_pk_add_f32 v[72:73], v[72:73], 1.0 op_sel_hi:[1,0]
	v_pk_add_f32 v[74:75], v[74:75], 1.0 op_sel_hi:[1,0]
	v_rcp_f32_e32 v76, v76
	v_rcp_f32_e32 v77, v77
	v_rcp_f32_e32 v78, v78
	v_rcp_f32_e32 v79, v79
	v_rcp_f32_e32 v72, v72
	v_rcp_f32_e32 v73, v73
	v_rcp_f32_e32 v74, v74
	v_rcp_f32_e32 v75, v75
	v_lshlrev_b32_e32 v245, 1, v230
	v_sub_u32_e32 v245, v245, v247
	s_waitcnt vmcnt(26)
	v_lshlrev_b32_e32 v220, 16, v144
	v_and_b32_e32 v221, 0xffff0000, v144
	v_lshlrev_b32_e32 v222, 16, v148
	v_and_b32_e32 v223, 0xffff0000, v148
	v_pk_fma_f32 v[76:77], v[76:77], v[222:223], v[220:221]
	v_lshlrev_b32_e32 v220, 16, v145
	v_and_b32_e32 v221, 0xffff0000, v145
	v_lshlrev_b32_e32 v222, 16, v149
	v_and_b32_e32 v223, 0xffff0000, v149
	v_pk_fma_f32 v[78:79], v[78:79], v[222:223], v[220:221]
	v_lshlrev_b32_e32 v220, 16, v146
	v_and_b32_e32 v221, 0xffff0000, v146
	v_lshlrev_b32_e32 v222, 16, v150
	v_and_b32_e32 v223, 0xffff0000, v150
	v_pk_fma_f32 v[72:73], v[72:73], v[222:223], v[220:221]
	v_lshlrev_b32_e32 v220, 16, v147
	v_and_b32_e32 v221, 0xffff0000, v147
	v_lshlrev_b32_e32 v222, 16, v151
	v_and_b32_e32 v223, 0xffff0000, v151
	v_pk_fma_f32 v[74:75], v[74:75], v[222:223], v[220:221]
	s_nop 1
	v_permlane32_swap_b32_e32 v76, v72
	v_permlane32_swap_b32_e32 v77, v73
	v_permlane32_swap_b32_e32 v78, v74
	v_permlane32_swap_b32_e32 v79, v75
	global_store_dwordx4 v245, v[76:79], s[24:25]
	global_store_dwordx4 v245, v[72:75], s[24:25] offset:64
	global_load_dwordx4 v[144:147], v234, s[34:35]
	global_load_dwordx4 v[148:151], v234, s[46:47]
	v_mov_b32_e32 v224, v238
	v_pk_mul_f32 v[68:69], v[68:69], v[224:225] op_sel_hi:[1,0]
	v_pk_mul_f32 v[70:71], v[70:71], v[224:225] op_sel_hi:[1,0]
	v_pk_mul_f32 v[64:65], v[64:65], v[224:225] op_sel_hi:[1,0]
	v_pk_mul_f32 v[66:67], v[66:67], v[224:225] op_sel_hi:[1,0]
	v_exp_f32_e32 v68, v68
	v_exp_f32_e32 v69, v69
	v_exp_f32_e32 v70, v70
	v_exp_f32_e32 v71, v71
	v_exp_f32_e32 v64, v64
	v_exp_f32_e32 v65, v65
	v_exp_f32_e32 v66, v66
	v_exp_f32_e32 v67, v67
	v_pk_add_f32 v[68:69], v[68:69], 1.0 op_sel_hi:[1,0]
	v_pk_add_f32 v[70:71], v[70:71], 1.0 op_sel_hi:[1,0]
	v_pk_add_f32 v[64:65], v[64:65], 1.0 op_sel_hi:[1,0]
	v_pk_add_f32 v[66:67], v[66:67], 1.0 op_sel_hi:[1,0]
	v_rcp_f32_e32 v68, v68
	v_rcp_f32_e32 v69, v69
	v_rcp_f32_e32 v70, v70
	v_rcp_f32_e32 v71, v71
	v_rcp_f32_e32 v64, v64
	v_rcp_f32_e32 v65, v65
	v_rcp_f32_e32 v66, v66
	v_rcp_f32_e32 v67, v67
	v_lshlrev_b32_e32 v245, 1, v230
	v_sub_u32_e32 v245, v245, v247
	s_waitcnt vmcnt(28)
; __device__ __forceinline__ float fast_rcp(float x) { return __builtin_amdgcn_rcpf(x); }
;     __device__ __forceinline__ void operator()(const f32x4 (&acc)[2][2][4][2], const Unit& u, int wr, int wc, int fr, int fq) const {
;     ...
;                     const int m = 2 * mp + mm; const int r = row0 + ai * HALF + m * 16; const float nrs = rsv[ai][m] * -1.4426950408889634f;
; #pragma unroll
;                     for (int bj = 0; bj < 2; ++bj) {
;                         const size_t off = (size_t)r * 1024 + col0 + bj * HALF;
;                         const unsigned xw[4] = {xr[mm][bj].x, xr[mm][bj].y, xr[mm][bj].z, xr[mm][bj].w}, pw[4] = {pr[mm][bj].x, pr[mm][bj].y, pr[mm][bj].z, pr[mm][bj].w};
;                         f32x4 o[2];
; #pragma unroll
;                         for (int q = 0; q < 4; ++q) {
;                             const float t0 = acc[ai][bj][m][q >> 1][2 * (q & 1)] * nrs, t1 = acc[ai][bj][m][q >> 1][2 * (q & 1) + 1] * nrs;
;                             o[q >> 1][2 * (q & 1)] = __uint_as_float(xw[q] << 16) + fast_rcp(1.0f + __builtin_amdgcn_exp2f(t0)) * __uint_as_float(pw[q] << 16);
;                             o[q >> 1][2 * (q & 1) + 1] = __uint_as_float(xw[q] & 0xffff0000u) + fast_rcp(1.0f + __builtin_amdgcn_exp2f(t1)) * __uint_as_float(pw[q] & 0xffff0000u);
;                         }
;                         *(f32x4*)(Y + off) = o[0]; *(f32x4*)(Y + off + 4) = o[1];
	v_lshlrev_b32_e32 v220, 16, v152
	v_and_b32_e32 v221, 0xffff0000, v152
	v_lshlrev_b32_e32 v222, 16, v156
	v_and_b32_e32 v223, 0xffff0000, v156
	v_pk_fma_f32 v[68:69], v[68:69], v[222:223], v[220:221]
	v_lshlrev_b32_e32 v220, 16, v153
	v_and_b32_e32 v221, 0xffff0000, v153
	v_lshlrev_b32_e32 v222, 16, v157
	v_and_b32_e32 v223, 0xffff0000, v157
	v_pk_fma_f32 v[70:71], v[70:71], v[222:223], v[220:221]
	v_lshlrev_b32_e32 v220, 16, v154
	v_and_b32_e32 v221, 0xffff0000, v154
	v_lshlrev_b32_e32 v222, 16, v158
	v_and_b32_e32 v223, 0xffff0000, v158
	v_pk_fma_f32 v[64:65], v[64:65], v[222:223], v[220:221]
	v_lshlrev_b32_e32 v220, 16, v155
	v_and_b32_e32 v221, 0xffff0000, v155
	v_lshlrev_b32_e32 v222, 16, v159
	v_and_b32_e32 v223, 0xffff0000, v159
	v_pk_fma_f32 v[66:67], v[66:67], v[222:223], v[220:221]
	s_nop 1
	v_permlane32_swap_b32_e32 v68, v64
	v_permlane32_swap_b32_e32 v69, v65
	v_permlane32_swap_b32_e32 v70, v66
	v_permlane32_swap_b32_e32 v71, v67
	global_store_dwordx4 v245, v[68:71], s[24:25] offset:512
	global_store_dwordx4 v245, v[64:67], s[24:25] offset:576
	global_load_dwordx4 v[152:155], v234, s[34:35] offset:256
	global_load_dwordx4 v[156:159], v234, s[46:47] offset:256
	v_mov_b32_e32 v224, v239
	v_pk_mul_f32 v[60:61], v[60:61], v[224:225] op_sel_hi:[1,0]
	v_pk_mul_f32 v[62:63], v[62:63], v[224:225] op_sel_hi:[1,0]
	v_pk_mul_f32 v[56:57], v[56:57], v[224:225] op_sel_hi:[1,0]
	v_pk_mul_f32 v[58:59], v[58:59], v[224:225] op_sel_hi:[1,0]
	v_exp_f32_e32 v60, v60
	v_exp_f32_e32 v61, v61
	v_exp_f32_e32 v62, v62
	v_exp_f32_e32 v63, v63
	v_exp_f32_e32 v56, v56
	v_exp_f32_e32 v57, v57
	v_exp_f32_e32 v58, v58
	v_exp_f32_e32 v59, v59
	v_pk_add_f32 v[60:61], v[60:61], 1.0 op_sel_hi:[1,0]
	v_pk_add_f32 v[62:63], v[62:63], 1.0 op_sel_hi:[1,0]
	v_pk_add_f32 v[56:57], v[56:57], 1.0 op_sel_hi:[1,0]
	v_pk_add_f32 v[58:59], v[58:59], 1.0 op_sel_hi:[1,0]
	v_rcp_f32_e32 v60, v60
	v_rcp_f32_e32 v61, v61
	v_rcp_f32_e32 v62, v62
	v_rcp_f32_e32 v63, v63
	v_rcp_f32_e32 v56, v56
	v_rcp_f32_e32 v57, v57
	v_rcp_f32_e32 v58, v58
	v_rcp_f32_e32 v59, v59
	v_lshlrev_b32_e32 v245, 1, v231
	v_sub_u32_e32 v245, v245, v247
	s_waitcnt vmcnt(28)
	v_lshlrev_b32_e32 v220, 16, v160
	v_and_b32_e32 v221, 0xffff0000, v160
	v_lshlrev_b32_e32 v222, 16, v164
	v_and_b32_e32 v223, 0xffff0000, v164
	v_pk_fma_f32 v[60:61], v[60:61], v[222:223], v[220:221]
	v_lshlrev_b32_e32 v220, 16, v161
	v_and_b32_e32 v221, 0xffff0000, v161
	v_lshlrev_b32_e32 v222, 16, v165
	v_and_b32_e32 v223, 0xffff0000, v165
	v_pk_fma_f32 v[62:63], v[62:63], v[222:223], v[220:221]
	v_lshlrev_b32_e32 v220, 16, v162
	v_and_b32_e32 v221, 0xffff0000, v162
	v_lshlrev_b32_e32 v222, 16, v166
	v_and_b32_e32 v223, 0xffff0000, v166
	v_pk_fma_f32 v[56:57], v[56:57], v[222:223], v[220:221]
	v_lshlrev_b32_e32 v220, 16, v163
	v_and_b32_e32 v221, 0xffff0000, v163
	v_lshlrev_b32_e32 v222, 16, v167
	v_and_b32_e32 v223, 0xffff0000, v167
	v_pk_fma_f32 v[58:59], v[58:59], v[222:223], v[220:221]
	s_nop 1
	v_permlane32_swap_b32_e32 v60, v56
	v_permlane32_swap_b32_e32 v61, v57
	v_permlane32_swap_b32_e32 v62, v58
	v_permlane32_swap_b32_e32 v63, v59
	global_store_dwordx4 v245, v[60:63], s[24:25]
	global_store_dwordx4 v245, v[56:59], s[24:25] offset:64
	v_mov_b32_e32 v224, v239
	v_pk_mul_f32 v[52:53], v[52:53], v[224:225] op_sel_hi:[1,0]
	v_pk_mul_f32 v[54:55], v[54:55], v[224:225] op_sel_hi:[1,0]
	v_pk_mul_f32 v[48:49], v[48:49], v[224:225] op_sel_hi:[1,0]
	v_pk_mul_f32 v[50:51], v[50:51], v[224:225] op_sel_hi:[1,0]
	v_exp_f32_e32 v52, v52
	v_exp_f32_e32 v53, v53
	v_exp_f32_e32 v54, v54
	v_exp_f32_e32 v55, v55
	v_exp_f32_e32 v48, v48
	v_exp_f32_e32 v49, v49
	v_exp_f32_e32 v50, v50
	v_exp_f32_e32 v51, v51
	v_pk_add_f32 v[52:53], v[52:53], 1.0 op_sel_hi:[1,0]
	v_pk_add_f32 v[54:55], v[54:55], 1.0 op_sel_hi:[1,0]
	v_pk_add_f32 v[48:49], v[48:49], 1.0 op_sel_hi:[1,0]
	v_pk_add_f32 v[50:51], v[50:51], 1.0 op_sel_hi:[1,0]
	v_rcp_f32_e32 v52, v52
	v_rcp_f32_e32 v53, v53
	v_rcp_f32_e32 v54, v54
	v_rcp_f32_e32 v55, v55
	v_rcp_f32_e32 v48, v48
	v_rcp_f32_e32 v49, v49
	v_rcp_f32_e32 v50, v50
	v_rcp_f32_e32 v51, v51
	v_lshlrev_b32_e32 v245, 1, v231
	v_sub_u32_e32 v245, v245, v247
	s_waitcnt vmcnt(26)
	v_lshlrev_b32_e32 v220, 16, v168
	v_and_b32_e32 v221, 0xffff0000, v168
	v_lshlrev_b32_e32 v222, 16, v172
	v_and_b32_e32 v223, 0xffff0000, v172
	v_pk_fma_f32 v[52:53], v[52:53], v[222:223], v[220:221]
	v_lshlrev_b32_e32 v220, 16, v169
	v_and_b32_e32 v221, 0xffff0000, v169
	v_lshlrev_b32_e32 v222, 16, v173
	v_and_b32_e32 v223, 0xffff0000, v173
	v_pk_fma_f32 v[54:55], v[54:55], v[222:223], v[220:221]
	v_lshlrev_b32_e32 v220, 16, v170
	v_and_b32_e32 v221, 0xffff0000, v170
	v_lshlrev_b32_e32 v222, 16, v174
	v_and_b32_e32 v223, 0xffff0000, v174
	v_pk_fma_f32 v[48:49], v[48:49], v[222:223], v[220:221]
	v_lshlrev_b32_e32 v220, 16, v171
	v_and_b32_e32 v221, 0xffff0000, v171
	v_lshlrev_b32_e32 v222, 16, v175
	v_and_b32_e32 v223, 0xffff0000, v175
	v_pk_fma_f32 v[50:51], v[50:51], v[222:223], v[220:221]
	s_nop 1
	v_permlane32_swap_b32_e32 v52, v48
	v_permlane32_swap_b32_e32 v53, v49
	v_permlane32_swap_b32_e32 v54, v50
	v_permlane32_swap_b32_e32 v55, v51
	global_store_dwordx4 v245, v[52:55], s[24:25] offset:512
	global_store_dwordx4 v245, v[48:51], s[24:25] offset:576
	v_mov_b32_e32 v224, v240
	v_pk_mul_f32 v[44:45], v[44:45], v[224:225] op_sel_hi:[1,0]
	v_pk_mul_f32 v[46:47], v[46:47], v[224:225] op_sel_hi:[1,0]
	v_pk_mul_f32 v[40:41], v[40:41], v[224:225] op_sel_hi:[1,0]
	v_pk_mul_f32 v[42:43], v[42:43], v[224:225] op_sel_hi:[1,0]
	v_exp_f32_e32 v44, v44
	v_exp_f32_e32 v45, v45
	v_exp_f32_e32 v46, v46
	v_exp_f32_e32 v47, v47
	v_exp_f32_e32 v40, v40
	v_exp_f32_e32 v41, v41
	v_exp_f32_e32 v42, v42
	v_exp_f32_e32 v43, v43
	v_pk_add_f32 v[44:45], v[44:45], 1.0 op_sel_hi:[1,0]
	v_pk_add_f32 v[46:47], v[46:47], 1.0 op_sel_hi:[1,0]
	v_pk_add_f32 v[40:41], v[40:41], 1.0 op_sel_hi:[1,0]
	v_pk_add_f32 v[42:43], v[42:43], 1.0 op_sel_hi:[1,0]
	v_rcp_f32_e32 v44, v44
	v_rcp_f32_e32 v45, v45
	v_rcp_f32_e32 v46, v46
	v_rcp_f32_e32 v47, v47
	v_rcp_f32_e32 v40, v40
	v_rcp_f32_e32 v41, v41
	v_rcp_f32_e32 v42, v42
	v_rcp_f32_e32 v43, v43
	v_lshlrev_b32_e32 v245, 1, v232
	v_sub_u32_e32 v245, v245, v247
	s_waitcnt vmcnt(24)
; __device__ __forceinline__ float fast_rcp(float x) { return __builtin_amdgcn_rcpf(x); }
;     __device__ __forceinline__ void operator()(const f32x4 (&acc)[2][2][4][2], const Unit& u, int wr, int wc, int fr, int fq) const {
;     ...
;                     const int m = 2 * mp + mm; const int r = row0 + ai * HALF + m * 16; const float nrs = rsv[ai][m] * -1.4426950408889634f;
; #pragma unroll
;                     for (int bj = 0; bj < 2; ++bj) {
;                         const size_t off = (size_t)r * 1024 + col0 + bj * HALF;
;                         const unsigned xw[4] = {xr[mm][bj].x, xr[mm][bj].y, xr[mm][bj].z, xr[mm][bj].w}, pw[4] = {pr[mm][bj].x, pr[mm][bj].y, pr[mm][bj].z, pr[mm][bj].w};
;                         f32x4 o[2];
; #pragma unroll
;                         for (int q = 0; q < 4; ++q) {
;                             const float t0 = acc[ai][bj][m][q >> 1][2 * (q & 1)] * nrs, t1 = acc[ai][bj][m][q >> 1][2 * (q & 1) + 1] * nrs;
;                             o[q >> 1][2 * (q & 1)] = __uint_as_float(xw[q] << 16) + fast_rcp(1.0f + __builtin_amdgcn_exp2f(t0)) * __uint_as_float(pw[q] << 16);
;                             o[q >> 1][2 * (q & 1) + 1] = __uint_as_float(xw[q] & 0xffff0000u) + fast_rcp(1.0f + __builtin_amdgcn_exp2f(t1)) * __uint_as_float(pw[q] & 0xffff0000u);
;                         }
;                         *(f32x4*)(Y + off) = o[0]; *(f32x4*)(Y + off + 4) = o[1];
	v_lshlrev_b32_e32 v220, 16, v196
	v_and_b32_e32 v221, 0xffff0000, v196
	v_lshlrev_b32_e32 v222, 16, v200
	v_and_b32_e32 v223, 0xffff0000, v200
	v_pk_fma_f32 v[44:45], v[44:45], v[222:223], v[220:221]
	v_lshlrev_b32_e32 v220, 16, v197
	v_and_b32_e32 v221, 0xffff0000, v197
	v_lshlrev_b32_e32 v222, 16, v201
	v_and_b32_e32 v223, 0xffff0000, v201
	v_pk_fma_f32 v[46:47], v[46:47], v[222:223], v[220:221]
	v_lshlrev_b32_e32 v220, 16, v198
	v_and_b32_e32 v221, 0xffff0000, v198
	v_lshlrev_b32_e32 v222, 16, v202
	v_and_b32_e32 v223, 0xffff0000, v202
	v_pk_fma_f32 v[40:41], v[40:41], v[222:223], v[220:221]
	v_lshlrev_b32_e32 v220, 16, v199
	v_and_b32_e32 v221, 0xffff0000, v199
	v_lshlrev_b32_e32 v222, 16, v203
	v_and_b32_e32 v223, 0xffff0000, v203
	v_pk_fma_f32 v[42:43], v[42:43], v[222:223], v[220:221]
	s_nop 1
	v_permlane32_swap_b32_e32 v44, v40
	v_permlane32_swap_b32_e32 v45, v41
	v_permlane32_swap_b32_e32 v46, v42
	v_permlane32_swap_b32_e32 v47, v43
	global_store_dwordx4 v245, v[44:47], s[24:25]
	global_store_dwordx4 v245, v[40:43], s[24:25] offset:64
	v_mov_b32_e32 v224, v240
	v_pk_mul_f32 v[36:37], v[36:37], v[224:225] op_sel_hi:[1,0]
	v_pk_mul_f32 v[38:39], v[38:39], v[224:225] op_sel_hi:[1,0]
	v_pk_mul_f32 v[32:33], v[32:33], v[224:225] op_sel_hi:[1,0]
	v_pk_mul_f32 v[34:35], v[34:35], v[224:225] op_sel_hi:[1,0]
	v_exp_f32_e32 v36, v36
	v_exp_f32_e32 v37, v37
	v_exp_f32_e32 v38, v38
	v_exp_f32_e32 v39, v39
	v_exp_f32_e32 v32, v32
	v_exp_f32_e32 v33, v33
	v_exp_f32_e32 v34, v34
	v_exp_f32_e32 v35, v35
	v_pk_add_f32 v[36:37], v[36:37], 1.0 op_sel_hi:[1,0]
	v_pk_add_f32 v[38:39], v[38:39], 1.0 op_sel_hi:[1,0]
	v_pk_add_f32 v[32:33], v[32:33], 1.0 op_sel_hi:[1,0]
	v_pk_add_f32 v[34:35], v[34:35], 1.0 op_sel_hi:[1,0]
	v_rcp_f32_e32 v36, v36
	v_rcp_f32_e32 v37, v37
	v_rcp_f32_e32 v38, v38
	v_rcp_f32_e32 v39, v39
	v_rcp_f32_e32 v32, v32
	v_rcp_f32_e32 v33, v33
	v_rcp_f32_e32 v34, v34
	v_rcp_f32_e32 v35, v35
	v_lshlrev_b32_e32 v245, 1, v232
	v_sub_u32_e32 v245, v245, v247
	s_waitcnt vmcnt(22)
	v_lshlrev_b32_e32 v220, 16, v204
	v_and_b32_e32 v221, 0xffff0000, v204
	v_lshlrev_b32_e32 v222, 16, v208
	v_and_b32_e32 v223, 0xffff0000, v208
	v_pk_fma_f32 v[36:37], v[36:37], v[222:223], v[220:221]
	v_lshlrev_b32_e32 v220, 16, v205
	v_and_b32_e32 v221, 0xffff0000, v205
	v_lshlrev_b32_e32 v222, 16, v209
	v_and_b32_e32 v223, 0xffff0000, v209
	v_pk_fma_f32 v[38:39], v[38:39], v[222:223], v[220:221]
	v_lshlrev_b32_e32 v220, 16, v206
	v_and_b32_e32 v221, 0xffff0000, v206
	v_lshlrev_b32_e32 v222, 16, v210
	v_and_b32_e32 v223, 0xffff0000, v210
	v_pk_fma_f32 v[32:33], v[32:33], v[222:223], v[220:221]
	v_lshlrev_b32_e32 v220, 16, v207
	v_and_b32_e32 v221, 0xffff0000, v207
	v_lshlrev_b32_e32 v222, 16, v211
	v_and_b32_e32 v223, 0xffff0000, v211
	v_pk_fma_f32 v[34:35], v[34:35], v[222:223], v[220:221]
	s_nop 1
	v_permlane32_swap_b32_e32 v36, v32
	v_permlane32_swap_b32_e32 v37, v33
	v_permlane32_swap_b32_e32 v38, v34
	v_permlane32_swap_b32_e32 v39, v35
	global_store_dwordx4 v245, v[36:39], s[24:25] offset:512
	global_store_dwordx4 v245, v[32:35], s[24:25] offset:576
	v_mov_b32_e32 v224, v241
	v_pk_mul_f32 v[28:29], v[28:29], v[224:225] op_sel_hi:[1,0]
	v_pk_mul_f32 v[30:31], v[30:31], v[224:225] op_sel_hi:[1,0]
	v_pk_mul_f32 v[24:25], v[24:25], v[224:225] op_sel_hi:[1,0]
	v_pk_mul_f32 v[26:27], v[26:27], v[224:225] op_sel_hi:[1,0]
	v_exp_f32_e32 v28, v28
	v_exp_f32_e32 v29, v29
	v_exp_f32_e32 v30, v30
	v_exp_f32_e32 v31, v31
	v_exp_f32_e32 v24, v24
	v_exp_f32_e32 v25, v25
	v_exp_f32_e32 v26, v26
	v_exp_f32_e32 v27, v27
	v_pk_add_f32 v[28:29], v[28:29], 1.0 op_sel_hi:[1,0]
	v_pk_add_f32 v[30:31], v[30:31], 1.0 op_sel_hi:[1,0]
	v_pk_add_f32 v[24:25], v[24:25], 1.0 op_sel_hi:[1,0]
	v_pk_add_f32 v[26:27], v[26:27], 1.0 op_sel_hi:[1,0]
	v_rcp_f32_e32 v28, v28
	v_rcp_f32_e32 v29, v29
	v_rcp_f32_e32 v30, v30
	v_rcp_f32_e32 v31, v31
	v_rcp_f32_e32 v24, v24
	v_rcp_f32_e32 v25, v25
	v_rcp_f32_e32 v26, v26
	v_rcp_f32_e32 v27, v27
	v_lshlrev_b32_e32 v245, 1, v233
	v_sub_u32_e32 v245, v245, v247
	s_waitcnt vmcnt(20)
	v_lshlrev_b32_e32 v220, 16, v124
	v_and_b32_e32 v221, 0xffff0000, v124
	v_lshlrev_b32_e32 v222, 16, v132
	v_and_b32_e32 v223, 0xffff0000, v132
	v_pk_fma_f32 v[28:29], v[28:29], v[222:223], v[220:221]
	v_lshlrev_b32_e32 v220, 16, v125
	v_and_b32_e32 v221, 0xffff0000, v125
	v_lshlrev_b32_e32 v222, 16, v133
	v_and_b32_e32 v223, 0xffff0000, v133
	v_pk_fma_f32 v[30:31], v[30:31], v[222:223], v[220:221]
	v_lshlrev_b32_e32 v220, 16, v126
	v_and_b32_e32 v221, 0xffff0000, v126
	v_lshlrev_b32_e32 v222, 16, v134
	v_and_b32_e32 v223, 0xffff0000, v134
	v_pk_fma_f32 v[24:25], v[24:25], v[222:223], v[220:221]
	v_lshlrev_b32_e32 v220, 16, v127
	v_and_b32_e32 v221, 0xffff0000, v127
	v_lshlrev_b32_e32 v222, 16, v135
	v_and_b32_e32 v223, 0xffff0000, v135
	v_pk_fma_f32 v[26:27], v[26:27], v[222:223], v[220:221]
	s_nop 1
	v_permlane32_swap_b32_e32 v28, v24
	v_permlane32_swap_b32_e32 v29, v25
	v_permlane32_swap_b32_e32 v30, v26
	v_permlane32_swap_b32_e32 v31, v27
	global_store_dwordx4 v245, v[28:31], s[24:25]
	global_store_dwordx4 v245, v[24:27], s[24:25] offset:64
	v_mov_b32_e32 v224, v241
	v_pk_mul_f32 v[20:21], v[20:21], v[224:225] op_sel_hi:[1,0]
	v_pk_mul_f32 v[22:23], v[22:23], v[224:225] op_sel_hi:[1,0]
	v_pk_mul_f32 v[16:17], v[16:17], v[224:225] op_sel_hi:[1,0]
	v_pk_mul_f32 v[18:19], v[18:19], v[224:225] op_sel_hi:[1,0]
	v_exp_f32_e32 v20, v20
	v_exp_f32_e32 v21, v21
	v_exp_f32_e32 v22, v22
	v_exp_f32_e32 v23, v23
	v_exp_f32_e32 v16, v16
	v_exp_f32_e32 v17, v17
	v_exp_f32_e32 v18, v18
	v_exp_f32_e32 v19, v19
	v_pk_add_f32 v[20:21], v[20:21], 1.0 op_sel_hi:[1,0]
	v_pk_add_f32 v[22:23], v[22:23], 1.0 op_sel_hi:[1,0]
	v_pk_add_f32 v[16:17], v[16:17], 1.0 op_sel_hi:[1,0]
	v_pk_add_f32 v[18:19], v[18:19], 1.0 op_sel_hi:[1,0]
	v_rcp_f32_e32 v20, v20
	v_rcp_f32_e32 v21, v21
	v_rcp_f32_e32 v22, v22
	v_rcp_f32_e32 v23, v23
	v_rcp_f32_e32 v16, v16
	v_rcp_f32_e32 v17, v17
	v_rcp_f32_e32 v18, v18
	v_rcp_f32_e32 v19, v19
	v_lshlrev_b32_e32 v245, 1, v233
	v_sub_u32_e32 v245, v245, v247
	s_waitcnt vmcnt(18)
; __device__ __forceinline__ float fast_rcp(float x) { return __builtin_amdgcn_rcpf(x); }
; #define PG8_BAR __builtin_amdgcn_s_barrier()
;     __device__ __forceinline__ void operator()(const f32x4 (&acc)[2][2][4][2], const Unit& u, int wr, int wc, int fr, int fq) const {
;     ...
;                     const int m = 2 * mp + mm; const int r = row0 + ai * HALF + m * 16; const float nrs = rsv[ai][m] * -1.4426950408889634f;
; #pragma unroll
;                     for (int bj = 0; bj < 2; ++bj) {
;                         const size_t off = (size_t)r * 1024 + col0 + bj * HALF;
;                         const unsigned xw[4] = {xr[mm][bj].x, xr[mm][bj].y, xr[mm][bj].z, xr[mm][bj].w}, pw[4] = {pr[mm][bj].x, pr[mm][bj].y, pr[mm][bj].z, pr[mm][bj].w};
;                         f32x4 o[2];
; #pragma unroll
;                         for (int q = 0; q < 4; ++q) {
;                             const float t0 = acc[ai][bj][m][q >> 1][2 * (q & 1)] * nrs, t1 = acc[ai][bj][m][q >> 1][2 * (q & 1) + 1] * nrs;
;                             o[q >> 1][2 * (q & 1)] = __uint_as_float(xw[q] << 16) + fast_rcp(1.0f + __builtin_amdgcn_exp2f(t0)) * __uint_as_float(pw[q] << 16);
;                             o[q >> 1][2 * (q & 1) + 1] = __uint_as_float(xw[q] & 0xffff0000u) + fast_rcp(1.0f + __builtin_amdgcn_exp2f(t1)) * __uint_as_float(pw[q] & 0xffff0000u);
;                         }
;                         *(f32x4*)(Y + off) = o[0]; *(f32x4*)(Y + off + 4) = o[1];
; template <class Epi, class Sched, bool ALIGN_EPI = false, bool SP2 = false>
; __device__ __forceinline__ void gemm_phase(PG8_LAS unsigned char* lds, const Gemm g, const Sched& S, const Epi& E) {
;     ...
;         if constexpr (!Epi::AFTER_DRAIN) { E(acc, cur, wr, wc, fr, fq); S.done(cur); }
;         if (!has_next) break;
; #pragma unroll
;         for (int a = 0; a < 2; ++a)
; #pragma unroll
;             for (int b = 0; b < 2; ++b)
; #pragma unroll
;                 for (int m = 0; m < 4; ++m)
; #pragma unroll
;                     for (int n = 0; n < 2; ++n) acc[a][b][m][n] = (f32x4){0.f, 0.f, 0.f, 0.f};
;         cur = nxt; cA = nA; cB = nB; ++ui;
;         if constexpr (ALIGN_EPI) { if (wr == 1) PG8_BAR; }
;     }
	v_lshlrev_b32_e32 v220, 16, v136
	v_and_b32_e32 v221, 0xffff0000, v136
	v_lshlrev_b32_e32 v222, 16, v140
	v_and_b32_e32 v223, 0xffff0000, v140
	v_pk_fma_f32 v[20:21], v[20:21], v[222:223], v[220:221]
	v_lshlrev_b32_e32 v220, 16, v137
	v_and_b32_e32 v221, 0xffff0000, v137
	v_lshlrev_b32_e32 v222, 16, v141
	v_and_b32_e32 v223, 0xffff0000, v141
	v_pk_fma_f32 v[22:23], v[22:23], v[222:223], v[220:221]
	v_lshlrev_b32_e32 v220, 16, v138
	v_and_b32_e32 v221, 0xffff0000, v138
	v_lshlrev_b32_e32 v222, 16, v142
	v_and_b32_e32 v223, 0xffff0000, v142
	v_pk_fma_f32 v[16:17], v[16:17], v[222:223], v[220:221]
	v_lshlrev_b32_e32 v220, 16, v139
	v_and_b32_e32 v221, 0xffff0000, v139
	v_lshlrev_b32_e32 v222, 16, v143
	v_and_b32_e32 v223, 0xffff0000, v143
	v_pk_fma_f32 v[18:19], v[18:19], v[222:223], v[220:221]
	s_nop 1
	v_permlane32_swap_b32_e32 v20, v16
	v_permlane32_swap_b32_e32 v21, v17
	v_permlane32_swap_b32_e32 v22, v18
	v_permlane32_swap_b32_e32 v23, v19
	global_store_dwordx4 v245, v[20:23], s[24:25] offset:512
	global_store_dwordx4 v245, v[16:19], s[24:25] offset:576
	v_mov_b32_e32 v224, v242
	v_pk_mul_f32 v[12:13], v[12:13], v[224:225] op_sel_hi:[1,0]
	v_pk_mul_f32 v[14:15], v[14:15], v[224:225] op_sel_hi:[1,0]
	v_pk_mul_f32 v[8:9], v[8:9], v[224:225] op_sel_hi:[1,0]
	v_pk_mul_f32 v[10:11], v[10:11], v[224:225] op_sel_hi:[1,0]
	v_exp_f32_e32 v12, v12
	v_exp_f32_e32 v13, v13
	v_exp_f32_e32 v14, v14
	v_exp_f32_e32 v15, v15
	v_exp_f32_e32 v8, v8
	v_exp_f32_e32 v9, v9
	v_exp_f32_e32 v10, v10
	v_exp_f32_e32 v11, v11
	v_pk_add_f32 v[12:13], v[12:13], 1.0 op_sel_hi:[1,0]
	v_pk_add_f32 v[14:15], v[14:15], 1.0 op_sel_hi:[1,0]
	v_pk_add_f32 v[8:9], v[8:9], 1.0 op_sel_hi:[1,0]
	v_pk_add_f32 v[10:11], v[10:11], 1.0 op_sel_hi:[1,0]
	v_rcp_f32_e32 v12, v12
	v_rcp_f32_e32 v13, v13
	v_rcp_f32_e32 v14, v14
	v_rcp_f32_e32 v15, v15
	v_rcp_f32_e32 v8, v8
	v_rcp_f32_e32 v9, v9
	v_rcp_f32_e32 v10, v10
	v_rcp_f32_e32 v11, v11
	v_lshlrev_b32_e32 v245, 1, v234
	v_sub_u32_e32 v245, v245, v247
	s_waitcnt vmcnt(16)
	v_lshlrev_b32_e32 v220, 16, v144
	v_and_b32_e32 v221, 0xffff0000, v144
	v_lshlrev_b32_e32 v222, 16, v148
	v_and_b32_e32 v223, 0xffff0000, v148
	v_pk_fma_f32 v[12:13], v[12:13], v[222:223], v[220:221]
	v_lshlrev_b32_e32 v220, 16, v145
	v_and_b32_e32 v221, 0xffff0000, v145
	v_lshlrev_b32_e32 v222, 16, v149
	v_and_b32_e32 v223, 0xffff0000, v149
	v_pk_fma_f32 v[14:15], v[14:15], v[222:223], v[220:221]
	v_lshlrev_b32_e32 v220, 16, v146
	v_and_b32_e32 v221, 0xffff0000, v146
	v_lshlrev_b32_e32 v222, 16, v150
	v_and_b32_e32 v223, 0xffff0000, v150
	v_pk_fma_f32 v[8:9], v[8:9], v[222:223], v[220:221]
	v_lshlrev_b32_e32 v220, 16, v147
	v_and_b32_e32 v221, 0xffff0000, v147
	v_lshlrev_b32_e32 v222, 16, v151
	v_and_b32_e32 v223, 0xffff0000, v151
	v_pk_fma_f32 v[10:11], v[10:11], v[222:223], v[220:221]
	s_nop 1
	v_permlane32_swap_b32_e32 v12, v8
	v_permlane32_swap_b32_e32 v13, v9
	v_permlane32_swap_b32_e32 v14, v10
	v_permlane32_swap_b32_e32 v15, v11
	global_store_dwordx4 v245, v[12:15], s[24:25]
	global_store_dwordx4 v245, v[8:11], s[24:25] offset:64
	v_mov_b32_e32 v224, v242
	v_pk_mul_f32 v[4:5], v[4:5], v[224:225] op_sel_hi:[1,0]
	v_pk_mul_f32 v[6:7], v[6:7], v[224:225] op_sel_hi:[1,0]
	v_pk_mul_f32 v[0:1], v[0:1], v[224:225] op_sel_hi:[1,0]
	v_pk_mul_f32 v[2:3], v[2:3], v[224:225] op_sel_hi:[1,0]
	v_exp_f32_e32 v4, v4
	v_exp_f32_e32 v5, v5
	v_exp_f32_e32 v6, v6
	v_exp_f32_e32 v7, v7
	v_exp_f32_e32 v0, v0
	v_exp_f32_e32 v1, v1
	v_exp_f32_e32 v2, v2
	v_exp_f32_e32 v3, v3
	v_pk_add_f32 v[4:5], v[4:5], 1.0 op_sel_hi:[1,0]
	v_pk_add_f32 v[6:7], v[6:7], 1.0 op_sel_hi:[1,0]
	v_pk_add_f32 v[0:1], v[0:1], 1.0 op_sel_hi:[1,0]
	v_pk_add_f32 v[2:3], v[2:3], 1.0 op_sel_hi:[1,0]
	v_rcp_f32_e32 v4, v4
	v_rcp_f32_e32 v5, v5
	v_rcp_f32_e32 v6, v6
	v_rcp_f32_e32 v7, v7
	v_rcp_f32_e32 v0, v0
	v_rcp_f32_e32 v1, v1
	v_rcp_f32_e32 v2, v2
	v_rcp_f32_e32 v3, v3
	v_lshlrev_b32_e32 v245, 1, v234
	v_sub_u32_e32 v245, v245, v247
	s_waitcnt vmcnt(14)
	v_lshlrev_b32_e32 v220, 16, v152
	v_and_b32_e32 v221, 0xffff0000, v152
	v_lshlrev_b32_e32 v222, 16, v156
	v_and_b32_e32 v223, 0xffff0000, v156
	v_pk_fma_f32 v[4:5], v[4:5], v[222:223], v[220:221]
	v_lshlrev_b32_e32 v220, 16, v153
	v_and_b32_e32 v221, 0xffff0000, v153
	v_lshlrev_b32_e32 v222, 16, v157
	v_and_b32_e32 v223, 0xffff0000, v157
	v_pk_fma_f32 v[6:7], v[6:7], v[222:223], v[220:221]
	v_lshlrev_b32_e32 v220, 16, v154
	v_and_b32_e32 v221, 0xffff0000, v154
	v_lshlrev_b32_e32 v222, 16, v158
	v_and_b32_e32 v223, 0xffff0000, v158
	v_pk_fma_f32 v[0:1], v[0:1], v[222:223], v[220:221]
	v_lshlrev_b32_e32 v220, 16, v155
	v_and_b32_e32 v221, 0xffff0000, v155
	v_lshlrev_b32_e32 v222, 16, v159
	v_and_b32_e32 v223, 0xffff0000, v159
	v_pk_fma_f32 v[2:3], v[2:3], v[222:223], v[220:221]
	s_nop 1
	v_permlane32_swap_b32_e32 v4, v0
	v_permlane32_swap_b32_e32 v5, v1
	v_permlane32_swap_b32_e32 v6, v2
	v_permlane32_swap_b32_e32 v7, v3
	global_store_dwordx4 v245, v[4:7], s[24:25] offset:512
	global_store_dwordx4 v245, v[0:3], s[24:25] offset:576
	s_and_b64 vcc, exec, s[0:1]
	s_mov_b64 s[0:1], -1
	s_cbranch_vccnz .LBB0_1240
	s_andn2_b64 vcc, exec, s[12:13]
	s_cbranch_vccnz .LBB0_1239
	s_barrier
	s_branch .LBB0_1239
